# v5 + software-pipelined K=2816 gemm_small loop (3 rotating operand half-sets)
# speedup vs baseline: 1.0113x; 1.0001x over previous
; #define MFMA16(a, b, c) __builtin_amdgcn_mfma_f32_16x16x32_bf16((a), (b), (c), 0, 0, 0)
; DI void gemm_small(const bf16_t* __restrict__ A, const bf16_t* __restrict__ Bt, int K, bf16_t* __restrict__ Yo) {
;     ...
;         f32x4 acc = (f32x4){0.f, 0.f, 0.f, 0.f};
;         for (int k0 = 0; k0 < K; k0 += 256) {
;             uint4 av[8], bv[8];
; #pragma unroll
;             for (int j = 0; j < 8; ++j) { av[j] = *(const uint4*)(ap + k0 + 32 * j); bv[j] = *(const uint4*)(bp + k0 + 32 * j); }
; #pragma unroll
;             for (int j = 0; j < 8; ++j) acc = MFMA16(asbf(av[j]), asbf(bv[j]), acc);
;         }
.LBB0_1458:
	s_waitcnt vmcnt(0)
	v_lshl_add_u64 v[114:115], v[8:9], 0, v[6:7]
	v_lshl_add_u64 v[116:117], v[10:11], 0, v[6:7]
	v_add_co_u32_e32 v114, vcc, 0x7800000, v114
	s_nop 1
	v_addc_co_u32_e32 v115, vcc, 0, v115, vcc
	v_add_co_u32_e32 v116, vcc, 0x1690000, v116
	s_nop 1
	v_addc_co_u32_e32 v117, vcc, 0, v117, vcc
	global_load_dwordx4 v[18:21], v[114:115], off
	global_load_dwordx4 v[22:25], v[114:115], off offset:64
	global_load_dwordx4 v[26:29], v[114:115], off offset:128
	global_load_dwordx4 v[30:33], v[114:115], off offset:192
	global_load_dwordx4 v[34:37], v[116:117], off
	global_load_dwordx4 v[38:41], v[116:117], off offset:64
	global_load_dwordx4 v[42:45], v[116:117], off offset:128
	global_load_dwordx4 v[46:49], v[116:117], off offset:192
	global_load_dwordx4 v[50:53], v[114:115], off offset:256
	global_load_dwordx4 v[54:57], v[114:115], off offset:320
	global_load_dwordx4 v[58:61], v[114:115], off offset:384
	global_load_dwordx4 v[62:65], v[114:115], off offset:448
	global_load_dwordx4 v[66:69], v[116:117], off offset:256
	global_load_dwordx4 v[70:73], v[116:117], off offset:320
	global_load_dwordx4 v[74:77], v[116:117], off offset:384
	global_load_dwordx4 v[78:81], v[116:117], off offset:448
	v_lshl_add_u64 v[114:115], v[114:115], 0, s[56:57]
	v_lshl_add_u64 v[116:117], v[116:117], 0, s[56:57]
	global_load_dwordx4 v[82:85], v[114:115], off
	global_load_dwordx4 v[86:89], v[114:115], off offset:64
	global_load_dwordx4 v[90:93], v[114:115], off offset:128
	global_load_dwordx4 v[94:97], v[114:115], off offset:192
	global_load_dwordx4 v[98:101], v[116:117], off
	global_load_dwordx4 v[102:105], v[116:117], off offset:64
	global_load_dwordx4 v[106:109], v[116:117], off offset:128
	global_load_dwordx4 v[110:113], v[116:117], off offset:192
	s_waitcnt vmcnt(16)
	v_mfma_f32_16x16x32_bf16 v[0:3], v[18:21], v[34:37], v[0:3]
	v_mfma_f32_16x16x32_bf16 v[0:3], v[22:25], v[38:41], v[0:3]
	v_mfma_f32_16x16x32_bf16 v[0:3], v[26:29], v[42:45], v[0:3]
	v_mfma_f32_16x16x32_bf16 v[0:3], v[30:33], v[46:49], v[0:3]
	global_load_dwordx4 v[18:21], v[114:115], off offset:256
	global_load_dwordx4 v[22:25], v[114:115], off offset:320
	global_load_dwordx4 v[26:29], v[114:115], off offset:384
	global_load_dwordx4 v[30:33], v[114:115], off offset:448
	global_load_dwordx4 v[34:37], v[116:117], off offset:256
	global_load_dwordx4 v[38:41], v[116:117], off offset:320
	global_load_dwordx4 v[42:45], v[116:117], off offset:384
	global_load_dwordx4 v[46:49], v[116:117], off offset:448
	v_lshl_add_u64 v[114:115], v[114:115], 0, s[56:57]
	v_lshl_add_u64 v[116:117], v[116:117], 0, s[56:57]
	s_waitcnt vmcnt(16)
	v_mfma_f32_16x16x32_bf16 v[0:3], v[50:53], v[66:69], v[0:3]
	v_mfma_f32_16x16x32_bf16 v[0:3], v[54:57], v[70:73], v[0:3]
	v_mfma_f32_16x16x32_bf16 v[0:3], v[58:61], v[74:77], v[0:3]
	v_mfma_f32_16x16x32_bf16 v[0:3], v[62:65], v[78:81], v[0:3]
	global_load_dwordx4 v[50:53], v[114:115], off
	global_load_dwordx4 v[54:57], v[114:115], off offset:64
	global_load_dwordx4 v[58:61], v[114:115], off offset:128
	global_load_dwordx4 v[62:65], v[114:115], off offset:192
	global_load_dwordx4 v[66:69], v[116:117], off
	global_load_dwordx4 v[70:73], v[116:117], off offset:64
	global_load_dwordx4 v[74:77], v[116:117], off offset:128
	global_load_dwordx4 v[78:81], v[116:117], off offset:192
	s_waitcnt vmcnt(16)
	v_mfma_f32_16x16x32_bf16 v[0:3], v[82:85], v[98:101], v[0:3]
	v_mfma_f32_16x16x32_bf16 v[0:3], v[86:89], v[102:105], v[0:3]
	v_mfma_f32_16x16x32_bf16 v[0:3], v[90:93], v[106:109], v[0:3]
	v_mfma_f32_16x16x32_bf16 v[0:3], v[94:97], v[110:113], v[0:3]
	global_load_dwordx4 v[82:85], v[114:115], off offset:256
	global_load_dwordx4 v[86:89], v[114:115], off offset:320
	global_load_dwordx4 v[90:93], v[114:115], off offset:384
	global_load_dwordx4 v[94:97], v[114:115], off offset:448
	global_load_dwordx4 v[98:101], v[116:117], off offset:256
	global_load_dwordx4 v[102:105], v[116:117], off offset:320
	global_load_dwordx4 v[106:109], v[116:117], off offset:384
	global_load_dwordx4 v[110:113], v[116:117], off offset:448
	v_lshl_add_u64 v[114:115], v[114:115], 0, s[56:57]
	v_lshl_add_u64 v[116:117], v[116:117], 0, s[56:57]
	s_waitcnt vmcnt(16)
	v_mfma_f32_16x16x32_bf16 v[0:3], v[18:21], v[34:37], v[0:3]
	v_mfma_f32_16x16x32_bf16 v[0:3], v[22:25], v[38:41], v[0:3]
	v_mfma_f32_16x16x32_bf16 v[0:3], v[26:29], v[42:45], v[0:3]
	v_mfma_f32_16x16x32_bf16 v[0:3], v[30:33], v[46:49], v[0:3]
	global_load_dwordx4 v[18:21], v[114:115], off
	global_load_dwordx4 v[22:25], v[114:115], off offset:64
	global_load_dwordx4 v[26:29], v[114:115], off offset:128
	global_load_dwordx4 v[30:33], v[114:115], off offset:192
	global_load_dwordx4 v[34:37], v[116:117], off
	global_load_dwordx4 v[38:41], v[116:117], off offset:64
	global_load_dwordx4 v[42:45], v[116:117], off offset:128
	global_load_dwordx4 v[46:49], v[116:117], off offset:192
	s_waitcnt vmcnt(16)
	v_mfma_f32_16x16x32_bf16 v[0:3], v[50:53], v[66:69], v[0:3]
	v_mfma_f32_16x16x32_bf16 v[0:3], v[54:57], v[70:73], v[0:3]
	v_mfma_f32_16x16x32_bf16 v[0:3], v[58:61], v[74:77], v[0:3]
	v_mfma_f32_16x16x32_bf16 v[0:3], v[62:65], v[78:81], v[0:3]
	global_load_dwordx4 v[50:53], v[114:115], off offset:256
	global_load_dwordx4 v[54:57], v[114:115], off offset:320
	global_load_dwordx4 v[58:61], v[114:115], off offset:384
	global_load_dwordx4 v[62:65], v[114:115], off offset:448
	global_load_dwordx4 v[66:69], v[116:117], off offset:256
	global_load_dwordx4 v[70:73], v[116:117], off offset:320
	global_load_dwordx4 v[74:77], v[116:117], off offset:384
	global_load_dwordx4 v[78:81], v[116:117], off offset:448
	v_lshl_add_u64 v[114:115], v[114:115], 0, s[56:57]
	v_lshl_add_u64 v[116:117], v[116:117], 0, s[56:57]
	s_waitcnt vmcnt(16)
; #define MFMA16(a, b, c) __builtin_amdgcn_mfma_f32_16x16x32_bf16((a), (b), (c), 0, 0, 0)
; DI void gemm_small(const bf16_t* __restrict__ A, const bf16_t* __restrict__ Bt, int K, bf16_t* __restrict__ Yo) {
;     ...
;         f32x4 acc = (f32x4){0.f, 0.f, 0.f, 0.f};
;         for (int k0 = 0; k0 < K; k0 += 256) {
;             uint4 av[8], bv[8];
; #pragma unroll
;             for (int j = 0; j < 8; ++j) { av[j] = *(const uint4*)(ap + k0 + 32 * j); bv[j] = *(const uint4*)(bp + k0 + 32 * j); }
; #pragma unroll
;             for (int j = 0; j < 8; ++j) acc = MFMA16(asbf(av[j]), asbf(bv[j]), acc);
;         }
	v_mfma_f32_16x16x32_bf16 v[0:3], v[82:85], v[98:101], v[0:3]
	v_mfma_f32_16x16x32_bf16 v[0:3], v[86:89], v[102:105], v[0:3]
	v_mfma_f32_16x16x32_bf16 v[0:3], v[90:93], v[106:109], v[0:3]
	v_mfma_f32_16x16x32_bf16 v[0:3], v[94:97], v[110:113], v[0:3]
	global_load_dwordx4 v[82:85], v[114:115], off
	global_load_dwordx4 v[86:89], v[114:115], off offset:64
	global_load_dwordx4 v[90:93], v[114:115], off offset:128
	global_load_dwordx4 v[94:97], v[114:115], off offset:192
	global_load_dwordx4 v[98:101], v[116:117], off
	global_load_dwordx4 v[102:105], v[116:117], off offset:64
	global_load_dwordx4 v[106:109], v[116:117], off offset:128
	global_load_dwordx4 v[110:113], v[116:117], off offset:192
	s_waitcnt vmcnt(16)
	v_mfma_f32_16x16x32_bf16 v[0:3], v[18:21], v[34:37], v[0:3]
	v_mfma_f32_16x16x32_bf16 v[0:3], v[22:25], v[38:41], v[0:3]
	v_mfma_f32_16x16x32_bf16 v[0:3], v[26:29], v[42:45], v[0:3]
	v_mfma_f32_16x16x32_bf16 v[0:3], v[30:33], v[46:49], v[0:3]
	global_load_dwordx4 v[18:21], v[114:115], off offset:256
	global_load_dwordx4 v[22:25], v[114:115], off offset:320
	global_load_dwordx4 v[26:29], v[114:115], off offset:384
	global_load_dwordx4 v[30:33], v[114:115], off offset:448
	global_load_dwordx4 v[34:37], v[116:117], off offset:256
	global_load_dwordx4 v[38:41], v[116:117], off offset:320
	global_load_dwordx4 v[42:45], v[116:117], off offset:384
	global_load_dwordx4 v[46:49], v[116:117], off offset:448
	v_lshl_add_u64 v[114:115], v[114:115], 0, s[56:57]
	v_lshl_add_u64 v[116:117], v[116:117], 0, s[56:57]
	s_waitcnt vmcnt(16)
	v_mfma_f32_16x16x32_bf16 v[0:3], v[50:53], v[66:69], v[0:3]
	v_mfma_f32_16x16x32_bf16 v[0:3], v[54:57], v[70:73], v[0:3]
	v_mfma_f32_16x16x32_bf16 v[0:3], v[58:61], v[74:77], v[0:3]
	v_mfma_f32_16x16x32_bf16 v[0:3], v[62:65], v[78:81], v[0:3]
	global_load_dwordx4 v[50:53], v[114:115], off
	global_load_dwordx4 v[54:57], v[114:115], off offset:64
	global_load_dwordx4 v[58:61], v[114:115], off offset:128
	global_load_dwordx4 v[62:65], v[114:115], off offset:192
	global_load_dwordx4 v[66:69], v[116:117], off
	global_load_dwordx4 v[70:73], v[116:117], off offset:64
	global_load_dwordx4 v[74:77], v[116:117], off offset:128
	global_load_dwordx4 v[78:81], v[116:117], off offset:192
	s_waitcnt vmcnt(16)
	v_mfma_f32_16x16x32_bf16 v[0:3], v[82:85], v[98:101], v[0:3]
	v_mfma_f32_16x16x32_bf16 v[0:3], v[86:89], v[102:105], v[0:3]
	v_mfma_f32_16x16x32_bf16 v[0:3], v[90:93], v[106:109], v[0:3]
	v_mfma_f32_16x16x32_bf16 v[0:3], v[94:97], v[110:113], v[0:3]
	global_load_dwordx4 v[82:85], v[114:115], off offset:256
	global_load_dwordx4 v[86:89], v[114:115], off offset:320
	global_load_dwordx4 v[90:93], v[114:115], off offset:384
	global_load_dwordx4 v[94:97], v[114:115], off offset:448
	global_load_dwordx4 v[98:101], v[116:117], off offset:256
	global_load_dwordx4 v[102:105], v[116:117], off offset:320
	global_load_dwordx4 v[106:109], v[116:117], off offset:384
	global_load_dwordx4 v[110:113], v[116:117], off offset:448
	v_lshl_add_u64 v[114:115], v[114:115], 0, s[56:57]
	v_lshl_add_u64 v[116:117], v[116:117], 0, s[56:57]
	s_waitcnt vmcnt(16)
	v_mfma_f32_16x16x32_bf16 v[0:3], v[18:21], v[34:37], v[0:3]
	v_mfma_f32_16x16x32_bf16 v[0:3], v[22:25], v[38:41], v[0:3]
	v_mfma_f32_16x16x32_bf16 v[0:3], v[26:29], v[42:45], v[0:3]
	v_mfma_f32_16x16x32_bf16 v[0:3], v[30:33], v[46:49], v[0:3]
	global_load_dwordx4 v[18:21], v[114:115], off
	global_load_dwordx4 v[22:25], v[114:115], off offset:64
	global_load_dwordx4 v[26:29], v[114:115], off offset:128
	global_load_dwordx4 v[30:33], v[114:115], off offset:192
	global_load_dwordx4 v[34:37], v[116:117], off
	global_load_dwordx4 v[38:41], v[116:117], off offset:64
	global_load_dwordx4 v[42:45], v[116:117], off offset:128
	global_load_dwordx4 v[46:49], v[116:117], off offset:192
	s_waitcnt vmcnt(16)
	v_mfma_f32_16x16x32_bf16 v[0:3], v[50:53], v[66:69], v[0:3]
	v_mfma_f32_16x16x32_bf16 v[0:3], v[54:57], v[70:73], v[0:3]
	v_mfma_f32_16x16x32_bf16 v[0:3], v[58:61], v[74:77], v[0:3]
	v_mfma_f32_16x16x32_bf16 v[0:3], v[62:65], v[78:81], v[0:3]
	global_load_dwordx4 v[50:53], v[114:115], off offset:256
	global_load_dwordx4 v[54:57], v[114:115], off offset:320
	global_load_dwordx4 v[58:61], v[114:115], off offset:384
	global_load_dwordx4 v[62:65], v[114:115], off offset:448
	global_load_dwordx4 v[66:69], v[116:117], off offset:256
	global_load_dwordx4 v[70:73], v[116:117], off offset:320
	global_load_dwordx4 v[74:77], v[116:117], off offset:384
	global_load_dwordx4 v[78:81], v[116:117], off offset:448
	v_lshl_add_u64 v[114:115], v[114:115], 0, s[56:57]
	v_lshl_add_u64 v[116:117], v[116:117], 0, s[56:57]
	s_waitcnt vmcnt(16)
	v_mfma_f32_16x16x32_bf16 v[0:3], v[82:85], v[98:101], v[0:3]
	v_mfma_f32_16x16x32_bf16 v[0:3], v[86:89], v[102:105], v[0:3]
	v_mfma_f32_16x16x32_bf16 v[0:3], v[90:93], v[106:109], v[0:3]
	v_mfma_f32_16x16x32_bf16 v[0:3], v[94:97], v[110:113], v[0:3]
	global_load_dwordx4 v[82:85], v[114:115], off
	global_load_dwordx4 v[86:89], v[114:115], off offset:64
	global_load_dwordx4 v[90:93], v[114:115], off offset:128
	global_load_dwordx4 v[94:97], v[114:115], off offset:192
	global_load_dwordx4 v[98:101], v[116:117], off
	global_load_dwordx4 v[102:105], v[116:117], off offset:64
	global_load_dwordx4 v[106:109], v[116:117], off offset:128
	global_load_dwordx4 v[110:113], v[116:117], off offset:192
	s_waitcnt vmcnt(16)
; #define MFMA16(a, b, c) __builtin_amdgcn_mfma_f32_16x16x32_bf16((a), (b), (c), 0, 0, 0)
; DI void gemm_small(const bf16_t* __restrict__ A, const bf16_t* __restrict__ Bt, int K, bf16_t* __restrict__ Yo) {
;     ...
;         f32x4 acc = (f32x4){0.f, 0.f, 0.f, 0.f};
;         for (int k0 = 0; k0 < K; k0 += 256) {
;             uint4 av[8], bv[8];
; #pragma unroll
;             for (int j = 0; j < 8; ++j) { av[j] = *(const uint4*)(ap + k0 + 32 * j); bv[j] = *(const uint4*)(bp + k0 + 32 * j); }
; #pragma unroll
;             for (int j = 0; j < 8; ++j) acc = MFMA16(asbf(av[j]), asbf(bv[j]), acc);
;         }
	v_mfma_f32_16x16x32_bf16 v[0:3], v[18:21], v[34:37], v[0:3]
	v_mfma_f32_16x16x32_bf16 v[0:3], v[22:25], v[38:41], v[0:3]
	v_mfma_f32_16x16x32_bf16 v[0:3], v[26:29], v[42:45], v[0:3]
	v_mfma_f32_16x16x32_bf16 v[0:3], v[30:33], v[46:49], v[0:3]
	global_load_dwordx4 v[18:21], v[114:115], off offset:256
	global_load_dwordx4 v[22:25], v[114:115], off offset:320
	global_load_dwordx4 v[26:29], v[114:115], off offset:384
	global_load_dwordx4 v[30:33], v[114:115], off offset:448
	global_load_dwordx4 v[34:37], v[116:117], off offset:256
	global_load_dwordx4 v[38:41], v[116:117], off offset:320
	global_load_dwordx4 v[42:45], v[116:117], off offset:384
	global_load_dwordx4 v[46:49], v[116:117], off offset:448
	v_lshl_add_u64 v[114:115], v[114:115], 0, s[56:57]
	v_lshl_add_u64 v[116:117], v[116:117], 0, s[56:57]
	s_waitcnt vmcnt(16)
	v_mfma_f32_16x16x32_bf16 v[0:3], v[50:53], v[66:69], v[0:3]
	v_mfma_f32_16x16x32_bf16 v[0:3], v[54:57], v[70:73], v[0:3]
	v_mfma_f32_16x16x32_bf16 v[0:3], v[58:61], v[74:77], v[0:3]
	v_mfma_f32_16x16x32_bf16 v[0:3], v[62:65], v[78:81], v[0:3]
	global_load_dwordx4 v[50:53], v[114:115], off
	global_load_dwordx4 v[54:57], v[114:115], off offset:64
	global_load_dwordx4 v[58:61], v[114:115], off offset:128
	global_load_dwordx4 v[62:65], v[114:115], off offset:192
	global_load_dwordx4 v[66:69], v[116:117], off
	global_load_dwordx4 v[70:73], v[116:117], off offset:64
	global_load_dwordx4 v[74:77], v[116:117], off offset:128
	global_load_dwordx4 v[78:81], v[116:117], off offset:192
	s_waitcnt vmcnt(16)
	v_mfma_f32_16x16x32_bf16 v[0:3], v[82:85], v[98:101], v[0:3]
	v_mfma_f32_16x16x32_bf16 v[0:3], v[86:89], v[102:105], v[0:3]
	v_mfma_f32_16x16x32_bf16 v[0:3], v[90:93], v[106:109], v[0:3]
	v_mfma_f32_16x16x32_bf16 v[0:3], v[94:97], v[110:113], v[0:3]
	global_load_dwordx4 v[82:85], v[114:115], off offset:256
	global_load_dwordx4 v[86:89], v[114:115], off offset:320
	global_load_dwordx4 v[90:93], v[114:115], off offset:384
	global_load_dwordx4 v[94:97], v[114:115], off offset:448
	global_load_dwordx4 v[98:101], v[116:117], off offset:256
	global_load_dwordx4 v[102:105], v[116:117], off offset:320
	global_load_dwordx4 v[106:109], v[116:117], off offset:384
	global_load_dwordx4 v[110:113], v[116:117], off offset:448
	v_lshl_add_u64 v[114:115], v[114:115], 0, s[56:57]
	v_lshl_add_u64 v[116:117], v[116:117], 0, s[56:57]
	s_waitcnt vmcnt(16)
	v_mfma_f32_16x16x32_bf16 v[0:3], v[18:21], v[34:37], v[0:3]
	v_mfma_f32_16x16x32_bf16 v[0:3], v[22:25], v[38:41], v[0:3]
	v_mfma_f32_16x16x32_bf16 v[0:3], v[26:29], v[42:45], v[0:3]
	v_mfma_f32_16x16x32_bf16 v[0:3], v[30:33], v[46:49], v[0:3]
	global_load_dwordx4 v[18:21], v[114:115], off
	global_load_dwordx4 v[22:25], v[114:115], off offset:64
	global_load_dwordx4 v[26:29], v[114:115], off offset:128
	global_load_dwordx4 v[30:33], v[114:115], off offset:192
	global_load_dwordx4 v[34:37], v[116:117], off
	global_load_dwordx4 v[38:41], v[116:117], off offset:64
	global_load_dwordx4 v[42:45], v[116:117], off offset:128
	global_load_dwordx4 v[46:49], v[116:117], off offset:192
	s_waitcnt vmcnt(16)
	v_mfma_f32_16x16x32_bf16 v[0:3], v[50:53], v[66:69], v[0:3]
	v_mfma_f32_16x16x32_bf16 v[0:3], v[54:57], v[70:73], v[0:3]
	v_mfma_f32_16x16x32_bf16 v[0:3], v[58:61], v[74:77], v[0:3]
	v_mfma_f32_16x16x32_bf16 v[0:3], v[62:65], v[78:81], v[0:3]
	global_load_dwordx4 v[50:53], v[114:115], off offset:256
	global_load_dwordx4 v[54:57], v[114:115], off offset:320
	global_load_dwordx4 v[58:61], v[114:115], off offset:384
	global_load_dwordx4 v[62:65], v[114:115], off offset:448
	global_load_dwordx4 v[66:69], v[116:117], off offset:256
	global_load_dwordx4 v[70:73], v[116:117], off offset:320
	global_load_dwordx4 v[74:77], v[116:117], off offset:384
	global_load_dwordx4 v[78:81], v[116:117], off offset:448
	v_lshl_add_u64 v[114:115], v[114:115], 0, s[56:57]
	v_lshl_add_u64 v[116:117], v[116:117], 0, s[56:57]
	s_waitcnt vmcnt(16)
; #define MFMA16(a, b, c) __builtin_amdgcn_mfma_f32_16x16x32_bf16((a), (b), (c), 0, 0, 0)
; DI void gemm_small(const bf16_t* __restrict__ A, const bf16_t* __restrict__ Bt, int K, bf16_t* __restrict__ Yo) {
;     ...
;         f32x4 acc = (f32x4){0.f, 0.f, 0.f, 0.f};
;         for (int k0 = 0; k0 < K; k0 += 256) {
;             uint4 av[8], bv[8];
; #pragma unroll
;             for (int j = 0; j < 8; ++j) { av[j] = *(const uint4*)(ap + k0 + 32 * j); bv[j] = *(const uint4*)(bp + k0 + 32 * j); }
; #pragma unroll
;             for (int j = 0; j < 8; ++j) acc = MFMA16(asbf(av[j]), asbf(bv[j]), acc);
;         }
; #pragma unroll
;         for (int e = 0; e < 4; ++e) Yo[(size_t)(row + 4 * g + e) * 1024 + col + fr] = f2bf(acc[e]);
	v_mfma_f32_16x16x32_bf16 v[0:3], v[82:85], v[98:101], v[0:3]
	v_mfma_f32_16x16x32_bf16 v[0:3], v[86:89], v[102:105], v[0:3]
	v_mfma_f32_16x16x32_bf16 v[0:3], v[90:93], v[106:109], v[0:3]
	v_mfma_f32_16x16x32_bf16 v[0:3], v[94:97], v[110:113], v[0:3]
	global_load_dwordx4 v[82:85], v[114:115], off
	global_load_dwordx4 v[86:89], v[114:115], off offset:64
	global_load_dwordx4 v[90:93], v[114:115], off offset:128
	global_load_dwordx4 v[94:97], v[114:115], off offset:192
	global_load_dwordx4 v[98:101], v[116:117], off
	global_load_dwordx4 v[102:105], v[116:117], off offset:64
	global_load_dwordx4 v[106:109], v[116:117], off offset:128
	global_load_dwordx4 v[110:113], v[116:117], off offset:192
	s_waitcnt vmcnt(16)
	v_mfma_f32_16x16x32_bf16 v[0:3], v[18:21], v[34:37], v[0:3]
	v_mfma_f32_16x16x32_bf16 v[0:3], v[22:25], v[38:41], v[0:3]
	v_mfma_f32_16x16x32_bf16 v[0:3], v[26:29], v[42:45], v[0:3]
	v_mfma_f32_16x16x32_bf16 v[0:3], v[30:33], v[46:49], v[0:3]
	global_load_dwordx4 v[18:21], v[114:115], off offset:256
	global_load_dwordx4 v[22:25], v[114:115], off offset:320
	global_load_dwordx4 v[26:29], v[114:115], off offset:384
	global_load_dwordx4 v[30:33], v[114:115], off offset:448
	global_load_dwordx4 v[34:37], v[116:117], off offset:256
	global_load_dwordx4 v[38:41], v[116:117], off offset:320
	global_load_dwordx4 v[42:45], v[116:117], off offset:384
	global_load_dwordx4 v[46:49], v[116:117], off offset:448
	v_lshl_add_u64 v[114:115], v[114:115], 0, s[56:57]
	v_lshl_add_u64 v[116:117], v[116:117], 0, s[56:57]
	s_waitcnt vmcnt(16)
	v_mfma_f32_16x16x32_bf16 v[0:3], v[50:53], v[66:69], v[0:3]
	v_mfma_f32_16x16x32_bf16 v[0:3], v[54:57], v[70:73], v[0:3]
	v_mfma_f32_16x16x32_bf16 v[0:3], v[58:61], v[74:77], v[0:3]
	v_mfma_f32_16x16x32_bf16 v[0:3], v[62:65], v[78:81], v[0:3]
	s_waitcnt vmcnt(8)
	v_mfma_f32_16x16x32_bf16 v[0:3], v[82:85], v[98:101], v[0:3]
	v_mfma_f32_16x16x32_bf16 v[0:3], v[86:89], v[102:105], v[0:3]
	v_mfma_f32_16x16x32_bf16 v[0:3], v[90:93], v[106:109], v[0:3]
	v_mfma_f32_16x16x32_bf16 v[0:3], v[94:97], v[110:113], v[0:3]
	s_waitcnt vmcnt(0)
	v_mfma_f32_16x16x32_bf16 v[0:3], v[18:21], v[34:37], v[0:3]
	v_mfma_f32_16x16x32_bf16 v[0:3], v[22:25], v[38:41], v[0:3]
	v_mfma_f32_16x16x32_bf16 v[0:3], v[26:29], v[42:45], v[0:3]
	v_mfma_f32_16x16x32_bf16 v[0:3], v[30:33], v[46:49], v[0:3]
	s_nop 0
	v_or_b32_e32 v8, v16, v15
	v_lshlrev_b32_e32 v212, 1, v17
	v_ashrrev_i32_e32 v9, 31, v8
	v_lshl_add_u64 v[10:11], v[4:5], 0, v[212:213]
	v_lshlrev_b64 v[16:17], 11, v[8:9]
	s_nop 1
	v_cvt_pk_bf16_f32 v0, v0, s0
	v_lshl_add_u64 v[16:17], v[10:11], 0, v[16:17]
	global_store_short v[16:17], v0, off
	v_or_b32_e32 v0, 1, v8
	v_cvt_pk_bf16_f32 v9, v1, s0
	v_ashrrev_i32_e32 v1, 31, v0
	v_lshlrev_b64 v[0:1], 11, v[0:1]
	v_lshl_add_u64 v[0:1], v[10:11], 0, v[0:1]
	global_store_short v[0:1], v9, off
	v_or_b32_e32 v0, 2, v8
	v_ashrrev_i32_e32 v1, 31, v0
	v_lshlrev_b64 v[0:1], 11, v[0:1]
	v_cvt_pk_bf16_f32 v2, v2, s0
	v_lshl_add_u64 v[0:1], v[10:11], 0, v[0:1]
	global_store_short v[0:1], v2, off
	v_or_b32_e32 v0, 3, v8
	v_ashrrev_i32_e32 v1, 31, v0
	v_lshlrev_b64 v[0:1], 11, v[0:1]
	v_cvt_pk_bf16_f32 v2, v3, s0
	v_lshl_add_u64 v[0:1], v[10:11], 0, v[0:1]
	s_mov_b32 s1, s96
	global_store_short v[0:1], v2, off
	s_add_i32 s0, s1, s0
	s_cmpk_gt_i32 s0, 0xff
	s_cbranch_scc0 .LBB0_1457
